# M1 attention: one static s_setprio 1 for the GLA waves (4-7), which enter the attention later than their SIMD partners
# speedup vs baseline: 1.0093x; 1.0027x over previous
.LBB0_497:
	s_cmp_gt_i32 s3, 3
	s_cbranch_scc0 .Lmy_att_noprio
	s_setprio 1

.LBB0_545:
	v_cmp_lt_i32_e32 vcc, v213, v215
	v_ashrrev_i32_e32 v209, 31, v208
	s_waitcnt lgkmcnt(0)
	v_ashrrev_i32_e32 v207, 31, v206
	v_cndmask_b32_e32 v64, v217, v213, vcc
	v_lshlrev_b32_e32 v67, 2, v64
	ds_bpermute_b32 v65, v67, v248
	v_lshlrev_b32_e32 v64, 2, v246
	s_cmp_gt_u32 s2, 7
	s_waitcnt lgkmcnt(0)
	v_add_f32_e32 v66, v248, v65
	v_div_scale_f32 v68, s[4:5], v66, v66, 1.0
	v_rcp_f32_e32 v69, v68
	v_div_scale_f32 v70, vcc, 1.0, v66, 1.0
	v_ashrrev_i32_e32 v65, 31, v64
	v_fma_f32 v71, -v68, v69, 1.0
	v_fmac_f32_e32 v69, v71, v69
	v_mul_f32_e32 v71, v70, v69
	v_fma_f32 v72, -v68, v71, v70
	v_fmac_f32_e32 v71, v72, v69
	v_fma_f32 v68, -v68, v71, v70
	v_div_fmas_f32 v68, v68, v69, v71
	v_div_fixup_f32 v66, v68, v66, 1.0
	v_lshlrev_b64 v[68:69], 11, v[208:209]
	v_lshl_add_u64 v[68:69], s[22:23], 0, v[68:69]
	v_lshl_add_u64 v[68:69], v[68:69], 0, s[20:21]
	v_lshlrev_b64 v[64:65], 1, v[64:65]
	v_pk_mul_f32 v[32:33], v[32:33], v[66:67] op_sel_hi:[1,0]
	v_pk_mul_f32 v[34:35], v[34:35], v[66:67] op_sel_hi:[1,0]
	v_lshl_add_u64 v[68:69], v[68:69], 0, v[64:65]
	v_cvt_pk_bf16_f32 v32, v32, v33
	v_cvt_pk_bf16_f32 v33, v34, v35
	global_store_dwordx2 v[68:69], v[32:33], off offset:1088
	v_pk_mul_f32 v[32:33], v[36:37], v[66:67] op_sel_hi:[1,0]
	ds_bpermute_b32 v36, v67, v247
	v_pk_mul_f32 v[34:35], v[38:39], v[66:67] op_sel_hi:[1,0]
	v_cvt_pk_bf16_f32 v32, v32, v33
	v_cvt_pk_bf16_f32 v33, v34, v35
	global_store_dwordx2 v[68:69], v[32:33], off offset:1104
	s_waitcnt lgkmcnt(0)
	v_add_f32_e32 v36, v247, v36
	v_div_scale_f32 v37, s[4:5], v36, v36, 1.0
	v_pk_mul_f32 v[32:33], v[40:41], v[66:67] op_sel_hi:[1,0]
	v_pk_mul_f32 v[34:35], v[42:43], v[66:67] op_sel_hi:[1,0]
	v_rcp_f32_e32 v38, v37
	v_cvt_pk_bf16_f32 v32, v32, v33
	v_cvt_pk_bf16_f32 v33, v34, v35
	global_store_dwordx2 v[68:69], v[32:33], off offset:1120
	v_pk_mul_f32 v[32:33], v[44:45], v[66:67] op_sel_hi:[1,0]
	v_pk_mul_f32 v[34:35], v[46:47], v[66:67] op_sel_hi:[1,0]
	v_cvt_pk_bf16_f32 v32, v32, v33
	v_cvt_pk_bf16_f32 v33, v34, v35
	global_store_dwordx2 v[68:69], v[32:33], off offset:1136
	v_fma_f32 v32, -v37, v38, 1.0
	v_fmac_f32_e32 v38, v32, v38
	v_div_scale_f32 v32, vcc, 1.0, v36, 1.0
	v_mul_f32_e32 v33, v32, v38
	v_fma_f32 v34, -v37, v33, v32
	v_fmac_f32_e32 v33, v34, v38
	v_fma_f32 v32, -v37, v33, v32
	v_div_fmas_f32 v32, v32, v38, v33
	v_lshlrev_b64 v[34:35], 11, v[206:207]
	v_div_fixup_f32 v32, v32, v36, 1.0
	v_lshl_add_u64 v[34:35], s[22:23], 0, v[34:35]
	v_pk_mul_f32 v[48:49], v[48:49], v[66:67] op_sel_hi:[1,0]
	v_pk_mul_f32 v[50:51], v[50:51], v[66:67] op_sel_hi:[1,0]
	v_lshl_add_u64 v[34:35], v[34:35], 0, s[20:21]
	v_pk_mul_f32 v[16:17], v[16:17], v[32:33] op_sel_hi:[1,0]
	v_pk_mul_f32 v[18:19], v[18:19], v[32:33] op_sel_hi:[1,0]
	v_pk_mul_f32 v[0:1], v[0:1], v[32:33] op_sel_hi:[1,0]
	v_pk_mul_f32 v[2:3], v[2:3], v[32:33] op_sel_hi:[1,0]
	v_cvt_pk_bf16_f32 v48, v48, v49
	v_cvt_pk_bf16_f32 v49, v50, v51
	v_lshl_add_u64 v[34:35], v[34:35], 0, v[64:65]
	v_cvt_pk_bf16_f32 v16, v16, v17
	v_cvt_pk_bf16_f32 v17, v18, v19
	v_cvt_pk_bf16_f32 v0, v0, v1
	v_cvt_pk_bf16_f32 v1, v2, v3
	global_store_dwordx2 v[68:69], v[48:49], off offset:1024
	v_pk_mul_f32 v[48:49], v[52:53], v[66:67] op_sel_hi:[1,0]
	v_pk_mul_f32 v[50:51], v[54:55], v[66:67] op_sel_hi:[1,0]
	global_store_dwordx2 v[34:35], v[16:17], off offset:1024
	v_pk_mul_f32 v[16:17], v[20:21], v[32:33] op_sel_hi:[1,0]
	v_pk_mul_f32 v[18:19], v[22:23], v[32:33] op_sel_hi:[1,0]
	global_store_dwordx2 v[34:35], v[0:1], off offset:1088
	v_pk_mul_f32 v[0:1], v[4:5], v[32:33] op_sel_hi:[1,0]
	v_pk_mul_f32 v[2:3], v[6:7], v[32:33] op_sel_hi:[1,0]
	v_cvt_pk_bf16_f32 v48, v48, v49
	v_cvt_pk_bf16_f32 v49, v50, v51
	v_cvt_pk_bf16_f32 v16, v16, v17
	v_cvt_pk_bf16_f32 v17, v18, v19
	v_cvt_pk_bf16_f32 v0, v0, v1
	v_cvt_pk_bf16_f32 v1, v2, v3
	global_store_dwordx2 v[68:69], v[48:49], off offset:1040
	v_pk_mul_f32 v[48:49], v[56:57], v[66:67] op_sel_hi:[1,0]
	v_pk_mul_f32 v[50:51], v[58:59], v[66:67] op_sel_hi:[1,0]
	global_store_dwordx2 v[34:35], v[16:17], off offset:1040
	v_pk_mul_f32 v[16:17], v[24:25], v[32:33] op_sel_hi:[1,0]
	v_pk_mul_f32 v[18:19], v[26:27], v[32:33] op_sel_hi:[1,0]
	global_store_dwordx2 v[34:35], v[0:1], off offset:1104
	v_pk_mul_f32 v[0:1], v[8:9], v[32:33] op_sel_hi:[1,0]
	v_pk_mul_f32 v[2:3], v[10:11], v[32:33] op_sel_hi:[1,0]
	v_cvt_pk_bf16_f32 v48, v48, v49
	v_cvt_pk_bf16_f32 v49, v50, v51
	v_cvt_pk_bf16_f32 v16, v16, v17
	v_cvt_pk_bf16_f32 v17, v18, v19
	v_cvt_pk_bf16_f32 v0, v0, v1
	v_cvt_pk_bf16_f32 v1, v2, v3
	global_store_dwordx2 v[68:69], v[48:49], off offset:1056
	v_pk_mul_f32 v[48:49], v[60:61], v[66:67] op_sel_hi:[1,0]
	v_pk_mul_f32 v[50:51], v[62:63], v[66:67] op_sel_hi:[1,0]
	global_store_dwordx2 v[34:35], v[16:17], off offset:1056
	v_pk_mul_f32 v[16:17], v[28:29], v[32:33] op_sel_hi:[1,0]
	v_pk_mul_f32 v[18:19], v[30:31], v[32:33] op_sel_hi:[1,0]
	global_store_dwordx2 v[34:35], v[0:1], off offset:1120
	v_pk_mul_f32 v[0:1], v[12:13], v[32:33] op_sel_hi:[1,0]
	v_pk_mul_f32 v[2:3], v[14:15], v[32:33] op_sel_hi:[1,0]
	v_cvt_pk_bf16_f32 v48, v48, v49
	v_cvt_pk_bf16_f32 v49, v50, v51
	v_cvt_pk_bf16_f32 v16, v16, v17
	v_cvt_pk_bf16_f32 v17, v18, v19
	v_cvt_pk_bf16_f32 v0, v0, v1
	v_cvt_pk_bf16_f32 v1, v2, v3
	global_store_dwordx2 v[68:69], v[48:49], off offset:1072
	global_store_dwordx2 v[34:35], v[16:17], off offset:1072
	global_store_dwordx2 v[34:35], v[0:1], off offset:1136
	s_setprio 0
	s_cbranch_scc1 .LBB0_550
	s_mov_b32 s4, s72
	s_mov_b32 s5, s74
	s_waitcnt vmcnt(0)
	v_mbcnt_lo_u32_b32 v164, -1, 0
	v_mbcnt_hi_u32_b32 v164, -1, v164
	s_mov_b32 s6, s3
	s_mov_b64 s[4:5], s[0:1]
	s_load_dwordx2 s[30:31], s[4:5], 0x98
	s_mov_b64 s[4:5], s[0:1]
	s_load_dwordx2 s[22:23], s[4:5], 0x90
	s_mov_b64 s[4:5], s[0:1]
	s_mov_b64 s[4:5], s[0:1]
	s_cmp_gt_i32 s6, 3
	s_cselect_b64 s[34:35], -1, 0
	s_mov_b64 s[4:5], s[0:1]
	s_mov_b64 s[38:39], -1
	s_and_b64 vcc, exec, s[34:35]
	s_cbranch_vccz .LBB0_556
	s_mov_b64 s[4:5], s[0:1]
	s_cbranch_execz .LBB0_557
